# v38 plus remaining accumulator clears as 64-bit moves (315 pairs)
# speedup vs baseline: 1.0011x; 1.0011x over previous
; template <class Epi, class Sched, bool ALIGN_EPI = false, bool SP2 = false>
; __device__ __forceinline__ void gemm_phase(PG8_LAS unsigned char* lds, int tid_in, const Gemm g, const Sched& S, const Epi& E) {
;     ...
;         const bool has_next = S.next(ui + 1, nxt);
;         const char* nA = has_next ? (const char*)g.A + (size_t)nxt.pm * tstep : cA; const char* nB = has_next ? (const char*)g.Bt + (size_t)nxt.pn * tstep : cB;
;         for (int t = 0; t < nt; t += 2) {
;             const bool last = (t == nt - 2);
;             const char* a1 = cA + (size_t)(t + 1) * kstep;
;             const char* a2 = last ? nA : cA + (size_t)(t + 2) * kstep; const char* b2 = last ? nB : cB + (size_t)(t + 2) * kstep;
;             const char* a3 = a2 + kstep; const char* b3 = b2 + kstep;
;     ...
;         for (int a = 0; a < 2; ++a)
; #pragma unroll
;             for (int b = 0; b < 2; ++b)
; #pragma unroll
;                 for (int m = 0; m < 4; ++m)
; #pragma unroll
;                     for (int n = 0; n < 2; ++n) acc[a][b][m][n] = (f32x4){0.f, 0.f, 0.f, 0.f};
.LBB0_136:
	s_ashr_i32 s15, s14, 31
	s_lshl_b64 s[16:17], s[14:15], 19
	v_readlane_b32 s20, v253, 52
	v_readlane_b32 s21, v253, 53
	s_add_u32 s16, s20, s16
	s_addc_u32 s17, s21, s17
	s_and_b64 s[20:21], s[4:5], exec
	s_cselect_b32 s1, s17, s35
	s_cselect_b32 s15, s16, s34
	s_ashr_i32 s13, s12, 31
	s_lshl_b64 s[20:21], s[12:13], 19
	v_readlane_b32 s13, v254, 35
	s_add_u32 s30, s13, s20
	v_readlane_b32 s13, v254, 36
	s_addc_u32 s31, s13, s21
	s_and_b64 s[20:21], s[4:5], exec
	s_cselect_b32 s13, s31, s43
	s_cselect_b32 s20, s30, s42
	s_add_u32 s34, s34, 0x40080
	s_addc_u32 s35, s35, 0
	s_add_u32 s21, s42, 0x100
	v_mov_b32_e32 v0, 0
	s_addc_u32 s28, s43, 0
	s_mov_b32 s29, -2
	v_mov_b32_e32 v1, 0
	v_mov_b64_e32 v[2:3], 0
	v_mov_b64_e32 v[4:5], 0
	v_mov_b64_e32 v[6:7], 0
	v_mov_b64_e32 v[10:11], 0
	v_mov_b64_e32 v[12:13], 0
	v_mov_b64_e32 v[18:19], 0
	v_mov_b64_e32 v[20:21], 0
	v_mov_b64_e32 v[26:27], 0
	v_mov_b64_e32 v[28:29], 0
	s_waitcnt vmcnt(0)
	v_mov_b64_e32 v[34:35], 0
	v_mov_b64_e32 v[36:37], 0
	v_mov_b64_e32 v[42:43], 0
	v_mov_b64_e32 v[44:45], 0
	v_mov_b64_e32 v[50:51], 0
	v_mov_b64_e32 v[52:53], 0
	v_mov_b64_e32 v[14:15], 0
	v_mov_b64_e32 v[16:17], 0
	v_mov_b64_e32 v[22:23], 0
	v_mov_b64_e32 v[24:25], 0
	v_mov_b64_e32 v[30:31], 0
	v_mov_b64_e32 v[32:33], 0
	v_mov_b64_e32 v[38:39], 0
	v_mov_b64_e32 v[40:41], 0
	v_mov_b64_e32 v[46:47], 0
	v_mov_b64_e32 v[48:49], 0
	v_mov_b64_e32 v[54:55], 0
	v_mov_b64_e32 v[56:57], 0
	v_mov_b64_e32 v[58:59], 0
	v_mov_b64_e32 v[60:61], 0
	v_mov_b64_e32 v[62:63], 0
	v_mov_b64_e32 v[64:65], 0
	v_mov_b64_e32 v[66:67], 0
	v_mov_b64_e32 v[68:69], 0
	v_mov_b64_e32 v[70:71], 0
	v_mov_b64_e32 v[72:73], 0
	v_mov_b64_e32 v[74:75], 0
	v_mov_b64_e32 v[76:77], 0
	v_mov_b64_e32 v[82:83], 0
	v_mov_b64_e32 v[84:85], 0
	v_mov_b64_e32 v[90:91], 0
	v_mov_b64_e32 v[92:93], 0
	v_mov_b64_e32 v[98:99], 0
	v_mov_b64_e32 v[100:101], 0
	v_mov_b64_e32 v[106:107], 0
	v_mov_b64_e32 v[108:109], 0
	v_mov_b64_e32 v[114:115], 0
	v_mov_b64_e32 v[116:117], 0
	v_mov_b64_e32 v[78:79], 0
	v_mov_b64_e32 v[80:81], 0
	v_mov_b64_e32 v[86:87], 0
	v_mov_b64_e32 v[88:89], 0
	v_mov_b64_e32 v[94:95], 0
	v_mov_b64_e32 v[96:97], 0
	v_mov_b64_e32 v[102:103], 0
	v_mov_b64_e32 v[104:105], 0
	v_mov_b64_e32 v[110:111], 0
	v_mov_b64_e32 v[112:113], 0
	v_mov_b64_e32 v[118:119], 0
	v_mov_b64_e32 v[120:121], 0
	v_mov_b64_e32 v[122:123], 0
	v_mov_b64_e32 v[124:125], 0
	v_mov_b64_e32 v[126:127], 0
	v_mov_b64_e32 v[128:129], 0

; template <class Epi, class Sched, bool ALIGN_EPI = false, bool SP2 = false>
; __device__ __forceinline__ void gemm_phase(PG8_LAS unsigned char* lds, int tid_in, const Gemm g, const Sched& S, const Epi& E) {
;     ...
;         const bool has_next = S.next(ui + 1, nxt);
;         const char* nA = has_next ? (const char*)g.A + (size_t)nxt.pm * tstep : cA; const char* nB = has_next ? (const char*)g.Bt + (size_t)nxt.pn * tstep : cB;
;         for (int t = 0; t < nt; t += 2) {
;             const bool last = (t == nt - 2);
;             const char* a1 = cA + (size_t)(t + 1) * kstep;
;             const char* a2 = last ? nA : cA + (size_t)(t + 2) * kstep; const char* b2 = last ? nB : cB + (size_t)(t + 2) * kstep;
;             const char* a3 = a2 + kstep; const char* b3 = b2 + kstep;
;     ...
;         for (int a = 0; a < 2; ++a)
; #pragma unroll
;             for (int b = 0; b < 2; ++b)
; #pragma unroll
;                 for (int m = 0; m < 4; ++m)
; #pragma unroll
;                     for (int n = 0; n < 2; ++n) acc[a][b][m][n] = (f32x4){0.f, 0.f, 0.f, 0.f};
.LBB0_591:
	s_ashr_i32 s15, s14, 31
	s_lshl_b64 s[16:17], s[14:15], 18
	v_readlane_b32 s30, v253, 26
	v_readlane_b32 s31, v253, 27
	s_add_u32 s16, s30, s16
	s_addc_u32 s17, s31, s17
	s_and_b64 s[30:31], s[6:7], exec
	s_cselect_b32 s15, s17, s35
	s_cselect_b32 s53, s16, s34
	s_ashr_i32 s13, s12, 31
	s_lshl_b64 s[30:31], s[12:13], 18
	s_add_u32 s30, s0, s30
	s_addc_u32 s31, s1, s31
	s_and_b64 s[36:37], s[6:7], exec
	s_cselect_b32 s13, s31, s43
	s_cselect_b32 s38, s30, s42
	s_add_u32 s34, s34, 0x20080
	s_addc_u32 s35, s35, 0
	s_add_u32 s39, s42, 0x100
	v_mov_b32_e32 v0, 0
	s_addc_u32 s36, s43, 0
	s_mov_b32 s37, -2
	v_mov_b32_e32 v1, 0
	v_mov_b64_e32 v[2:3], 0
	v_mov_b64_e32 v[4:5], 0
	v_mov_b64_e32 v[6:7], 0
	v_mov_b64_e32 v[18:19], 0
	v_mov_b64_e32 v[20:21], 0
	v_mov_b64_e32 v[22:23], 0
	v_mov_b64_e32 v[24:25], 0
	s_waitcnt vmcnt(0)
	v_mov_b64_e32 v[34:35], 0
	v_mov_b64_e32 v[36:37], 0
	v_mov_b64_e32 v[38:39], 0
	v_mov_b64_e32 v[40:41], 0
	v_mov_b64_e32 v[50:51], 0
	v_mov_b64_e32 v[52:53], 0
	v_mov_b64_e32 v[54:55], 0
	v_mov_b64_e32 v[56:57], 0
	v_mov_b64_e32 v[10:11], 0
	v_mov_b64_e32 v[12:13], 0
	v_mov_b64_e32 v[14:15], 0
	v_mov_b64_e32 v[16:17], 0
	v_mov_b64_e32 v[26:27], 0
	v_mov_b64_e32 v[28:29], 0
	v_mov_b64_e32 v[30:31], 0
	v_mov_b64_e32 v[32:33], 0
	v_mov_b64_e32 v[42:43], 0
	v_mov_b64_e32 v[44:45], 0
	v_mov_b64_e32 v[46:47], 0
	v_mov_b64_e32 v[48:49], 0
	v_mov_b64_e32 v[58:59], 0
	v_mov_b64_e32 v[60:61], 0
	v_mov_b64_e32 v[62:63], 0
	v_mov_b64_e32 v[64:65], 0
	v_mov_b64_e32 v[66:67], 0
	v_mov_b64_e32 v[68:69], 0
	v_mov_b64_e32 v[70:71], 0
	v_mov_b64_e32 v[72:73], 0
	v_mov_b64_e32 v[82:83], 0
	v_mov_b64_e32 v[84:85], 0
	v_mov_b64_e32 v[86:87], 0
	v_mov_b64_e32 v[88:89], 0
	v_mov_b64_e32 v[98:99], 0
	v_mov_b64_e32 v[100:101], 0
	v_mov_b64_e32 v[102:103], 0
	v_mov_b64_e32 v[104:105], 0
	v_mov_b64_e32 v[114:115], 0
	v_mov_b64_e32 v[116:117], 0
	v_mov_b64_e32 v[122:123], 0
	v_mov_b64_e32 v[124:125], 0
	v_mov_b64_e32 v[74:75], 0
	v_mov_b64_e32 v[76:77], 0
	v_mov_b64_e32 v[78:79], 0
	v_mov_b64_e32 v[80:81], 0
	v_mov_b64_e32 v[90:91], 0
	v_mov_b64_e32 v[92:93], 0
	v_mov_b64_e32 v[94:95], 0
	v_mov_b64_e32 v[96:97], 0
	v_mov_b64_e32 v[106:107], 0
	v_mov_b64_e32 v[108:109], 0
	v_mov_b64_e32 v[110:111], 0
	v_mov_b64_e32 v[112:113], 0
	v_mov_b64_e32 v[142:143], 0
	v_mov_b64_e32 v[144:145], 0
	v_mov_b64_e32 v[146:147], 0
	v_mov_b64_e32 v[148:149], 0

; template <class Epi, class Sched, bool ALIGN_EPI = false, bool SP2 = false>
; __device__ __forceinline__ void gemm_phase(PG8_LAS unsigned char* lds, int tid_in, const Gemm g, const Sched& S, const Epi& E) {
;     ...
;         const bool has_next = S.next(ui + 1, nxt);
;         const char* nA = has_next ? (const char*)g.A + (size_t)nxt.pm * tstep : cA; const char* nB = has_next ? (const char*)g.Bt + (size_t)nxt.pn * tstep : cB;
;         for (int t = 0; t < nt; t += 2) {
;             const bool last = (t == nt - 2);
;             const char* a1 = cA + (size_t)(t + 1) * kstep;
;             const char* a2 = last ? nA : cA + (size_t)(t + 2) * kstep; const char* b2 = last ? nB : cB + (size_t)(t + 2) * kstep;
;             const char* a3 = a2 + kstep; const char* b3 = b2 + kstep;
;     ...
;         for (int a = 0; a < 2; ++a)
; #pragma unroll
;             for (int b = 0; b < 2; ++b)
; #pragma unroll
;                 for (int m = 0; m < 4; ++m)
; #pragma unroll
;                     for (int n = 0; n < 2; ++n) acc[a][b][m][n] = (f32x4){0.f, 0.f, 0.f, 0.f};
.LBB0_707:
	s_ashr_i32 s17, s16, 31
	s_lshl_b64 s[30:31], s[16:17], 19
	s_add_u32 s30, s46, s30
	s_addc_u32 s31, s47, s31
	s_and_b64 s[34:35], s[4:5], exec
	s_cselect_b32 s17, s31, s49
	s_cselect_b32 s96, s30, s48
	s_ashr_i32 s15, s14, 31
	s_lshl_b64 s[34:35], s[14:15], 19
	s_add_u32 s34, s33, s34
	s_addc_u32 s35, s60, s35
	s_and_b64 s[36:37], s[4:5], exec
	s_cselect_b32 s15, s35, s51
	s_cselect_b32 s38, s34, s50
	s_add_u32 s48, s48, 0x40080
	s_addc_u32 s49, s49, 0
	s_add_u32 s39, s50, 0x100
	v_mov_b32_e32 v0, 0
	s_addc_u32 s36, s51, 0
	s_mov_b32 s37, -2
	v_mov_b32_e32 v1, 0
	v_mov_b64_e32 v[2:3], 0
	v_mov_b64_e32 v[4:5], 0
	v_mov_b64_e32 v[6:7], 0
	v_mov_b64_e32 v[18:19], 0
	v_mov_b64_e32 v[20:21], 0
	v_mov_b64_e32 v[22:23], 0
	v_mov_b64_e32 v[24:25], 0
	s_waitcnt vmcnt(0)
	v_mov_b64_e32 v[34:35], 0
	v_mov_b64_e32 v[36:37], 0
	v_mov_b64_e32 v[38:39], 0
	v_mov_b64_e32 v[40:41], 0
	v_mov_b64_e32 v[50:51], 0
	v_mov_b64_e32 v[52:53], 0
	v_mov_b64_e32 v[54:55], 0
	v_mov_b64_e32 v[56:57], 0
	v_mov_b64_e32 v[10:11], 0
	v_mov_b64_e32 v[12:13], 0
	v_mov_b64_e32 v[14:15], 0
	v_mov_b64_e32 v[16:17], 0
	v_mov_b64_e32 v[26:27], 0
	v_mov_b64_e32 v[28:29], 0
	v_mov_b64_e32 v[30:31], 0
	v_mov_b64_e32 v[32:33], 0
	v_mov_b64_e32 v[42:43], 0
	v_mov_b64_e32 v[44:45], 0
	v_mov_b64_e32 v[46:47], 0
	v_mov_b64_e32 v[48:49], 0
	v_mov_b64_e32 v[58:59], 0
	v_mov_b64_e32 v[60:61], 0
	v_mov_b64_e32 v[62:63], 0
	v_mov_b64_e32 v[64:65], 0
	v_mov_b64_e32 v[66:67], 0
	v_mov_b64_e32 v[68:69], 0
	v_mov_b64_e32 v[70:71], 0
	v_mov_b64_e32 v[72:73], 0
	v_mov_b64_e32 v[82:83], 0
	v_mov_b64_e32 v[84:85], 0
	v_mov_b64_e32 v[86:87], 0
	v_mov_b64_e32 v[88:89], 0
	v_mov_b64_e32 v[98:99], 0
	v_mov_b64_e32 v[100:101], 0
	v_mov_b64_e32 v[102:103], 0
	v_mov_b64_e32 v[104:105], 0
	v_mov_b64_e32 v[114:115], 0
	v_mov_b64_e32 v[116:117], 0
	v_mov_b64_e32 v[118:119], 0
	v_mov_b64_e32 v[120:121], 0
	v_mov_b64_e32 v[74:75], 0
	v_mov_b64_e32 v[76:77], 0
	v_mov_b64_e32 v[78:79], 0
	v_mov_b64_e32 v[80:81], 0
	v_mov_b64_e32 v[90:91], 0
	v_mov_b64_e32 v[92:93], 0
	v_mov_b64_e32 v[94:95], 0
	v_mov_b64_e32 v[96:97], 0
	v_mov_b64_e32 v[106:107], 0
	v_mov_b64_e32 v[108:109], 0
	v_mov_b64_e32 v[110:111], 0
	v_mov_b64_e32 v[112:113], 0
	v_mov_b64_e32 v[138:139], 0
	v_mov_b64_e32 v[140:141], 0
	v_mov_b64_e32 v[142:143], 0
	v_mov_b64_e32 v[144:145], 0

; template <class Epi, class Sched, bool ALIGN_EPI = false, bool SP2 = false>
; __device__ __forceinline__ void gemm_phase(PG8_LAS unsigned char* lds, int tid_in, const Gemm g, const Sched& S, const Epi& E) {
;     ...
;         const bool has_next = S.next(ui + 1, nxt);
;         const char* nA = has_next ? (const char*)g.A + (size_t)nxt.pm * tstep : cA; const char* nB = has_next ? (const char*)g.Bt + (size_t)nxt.pn * tstep : cB;
;         for (int t = 0; t < nt; t += 2) {
;             const bool last = (t == nt - 2);
;             const char* a1 = cA + (size_t)(t + 1) * kstep;
;             const char* a2 = last ? nA : cA + (size_t)(t + 2) * kstep; const char* b2 = last ? nB : cB + (size_t)(t + 2) * kstep;
;             const char* a3 = a2 + kstep; const char* b3 = b2 + kstep;
;     ...
;         for (int a = 0; a < 2; ++a)
; #pragma unroll
;             for (int b = 0; b < 2; ++b)
; #pragma unroll
;                 for (int m = 0; m < 4; ++m)
; #pragma unroll
;                     for (int n = 0; n < 2; ++n) acc[a][b][m][n] = (f32x4){0.f, 0.f, 0.f, 0.f};
.LBB0_834:
	s_ashr_i32 s17, s16, 31
	s_lshl_b64 s[8:9], s[16:17], 19
	v_readlane_b32 s30, v253, 52
	v_readlane_b32 s31, v253, 53
	s_add_u32 s8, s30, s8
	s_addc_u32 s9, s31, s9
	s_and_b64 s[30:31], s[4:5], exec
	s_cselect_b32 s17, s9, s35
	s_cselect_b32 s53, s8, s34
	s_ashr_i32 s15, s14, 31
	s_lshl_b64 s[30:31], s[14:15], 19
	s_add_u32 s30, s33, s30
	s_addc_u32 s31, s40, s31
	s_and_b64 s[36:37], s[4:5], exec
	s_cselect_b32 s15, s31, s43
	s_cselect_b32 s38, s30, s42
	s_add_u32 s34, s34, 0x40080
	s_addc_u32 s35, s35, 0
	s_add_u32 s39, s42, 0x100
	v_mov_b32_e32 v0, 0
	s_addc_u32 s36, s43, 0
	s_mov_b32 s37, -2
	v_mov_b32_e32 v1, 0
	v_mov_b64_e32 v[2:3], 0
	v_mov_b64_e32 v[4:5], 0
	v_mov_b64_e32 v[6:7], 0
	v_mov_b64_e32 v[18:19], 0
	v_mov_b64_e32 v[20:21], 0
	v_mov_b64_e32 v[22:23], 0
	v_mov_b64_e32 v[24:25], 0
	s_waitcnt vmcnt(0)
	v_mov_b64_e32 v[34:35], 0
	v_mov_b64_e32 v[36:37], 0
	v_mov_b64_e32 v[38:39], 0
	v_mov_b64_e32 v[40:41], 0
	v_mov_b64_e32 v[50:51], 0
	v_mov_b64_e32 v[52:53], 0
	v_mov_b64_e32 v[54:55], 0
	v_mov_b64_e32 v[56:57], 0
	v_mov_b64_e32 v[10:11], 0
	v_mov_b64_e32 v[12:13], 0
	v_mov_b64_e32 v[14:15], 0
	v_mov_b64_e32 v[16:17], 0
	v_mov_b64_e32 v[26:27], 0
	v_mov_b64_e32 v[28:29], 0
	v_mov_b64_e32 v[30:31], 0
	v_mov_b64_e32 v[32:33], 0
	v_mov_b64_e32 v[42:43], 0
	v_mov_b64_e32 v[44:45], 0
	v_mov_b64_e32 v[46:47], 0
	v_mov_b64_e32 v[48:49], 0
	v_mov_b64_e32 v[58:59], 0
	v_mov_b64_e32 v[60:61], 0
	v_mov_b64_e32 v[62:63], 0
	v_mov_b64_e32 v[64:65], 0
	v_mov_b64_e32 v[66:67], 0
	v_mov_b64_e32 v[68:69], 0
	v_mov_b64_e32 v[70:71], 0
	v_mov_b64_e32 v[72:73], 0
	v_mov_b64_e32 v[82:83], 0
	v_mov_b64_e32 v[84:85], 0
	v_mov_b64_e32 v[86:87], 0
	v_mov_b64_e32 v[88:89], 0
	v_mov_b64_e32 v[98:99], 0
	v_mov_b64_e32 v[100:101], 0
	v_mov_b64_e32 v[102:103], 0
	v_mov_b64_e32 v[104:105], 0
	v_mov_b64_e32 v[130:131], 0
	v_mov_b64_e32 v[132:133], 0
	v_mov_b64_e32 v[134:135], 0
	v_mov_b64_e32 v[136:137], 0
	v_mov_b64_e32 v[74:75], 0
	v_mov_b64_e32 v[76:77], 0
	v_mov_b64_e32 v[78:79], 0
	v_mov_b64_e32 v[80:81], 0
	v_mov_b64_e32 v[90:91], 0
	v_mov_b64_e32 v[92:93], 0
	v_mov_b64_e32 v[94:95], 0
	v_mov_b64_e32 v[96:97], 0
	v_mov_b64_e32 v[122:123], 0
	v_mov_b64_e32 v[124:125], 0
	v_mov_b64_e32 v[126:127], 0
	v_mov_b64_e32 v[128:129], 0
	v_mov_b64_e32 v[138:139], 0
	v_mov_b64_e32 v[140:141], 0
	v_mov_b64_e32 v[142:143], 0
	v_mov_b64_e32 v[144:145], 0

; template <class Epi, class Sched, bool ALIGN_EPI = false, bool SP2 = false>
; __device__ __forceinline__ void gemm_phase(PG8_LAS unsigned char* lds, int tid_in, const Gemm g, const Sched& S, const Epi& E) {
;     ...
;         const bool has_next = S.next(ui + 1, nxt);
;         const char* nA = has_next ? (const char*)g.A + (size_t)nxt.pm * tstep : cA; const char* nB = has_next ? (const char*)g.Bt + (size_t)nxt.pn * tstep : cB;
;         for (int t = 0; t < nt; t += 2) {
;             const bool last = (t == nt - 2);
;             const char* a1 = cA + (size_t)(t + 1) * kstep;
;             const char* a2 = last ? nA : cA + (size_t)(t + 2) * kstep; const char* b2 = last ? nB : cB + (size_t)(t + 2) * kstep;
;             const char* a3 = a2 + kstep; const char* b3 = b2 + kstep;
;     ...
;         for (int a = 0; a < 2; ++a)
; #pragma unroll
;             for (int b = 0; b < 2; ++b)
; #pragma unroll
;                 for (int m = 0; m < 4; ++m)
; #pragma unroll
;                     for (int n = 0; n < 2; ++n) acc[a][b][m][n] = (f32x4){0.f, 0.f, 0.f, 0.f};
.LBB0_914:
	s_ashr_i32 s59, s58, 31
	s_lshl_b64 s[36:37], s[58:59], 21
	s_add_u32 s50, s47, s36
	s_addc_u32 s51, s97, s37
	s_and_b64 s[36:37], s[4:5], exec
	s_cselect_b32 s59, s51, s7
	s_cselect_b32 s38, s50, s6
	s_ashr_i32 s43, s42, 31
	s_lshl_b64 s[36:37], s[42:43], 21
	s_add_u32 s60, s57, s36
	s_addc_u32 s61, s33, s37
	s_and_b64 s[36:37], s[4:5], exec
	s_cselect_b32 s39, s61, s9
	s_cselect_b32 s43, s60, s8
	s_add_u32 s6, s6, 0x100080
	s_addc_u32 s7, s7, 0
	s_add_u32 s36, s8, 0x100
	v_mov_b32_e32 v0, 0
	s_addc_u32 s37, s9, 0
	s_mov_b32 s18, -2
	v_mov_b32_e32 v1, 0
	v_mov_b64_e32 v[2:3], 0
	v_mov_b64_e32 v[4:5], 0
	v_mov_b64_e32 v[6:7], 0
	v_mov_b64_e32 v[18:19], 0
	v_mov_b64_e32 v[20:21], 0
	v_mov_b64_e32 v[22:23], 0
	v_mov_b64_e32 v[24:25], 0
	s_waitcnt vmcnt(0)
	v_mov_b64_e32 v[34:35], 0
	v_mov_b64_e32 v[36:37], 0
	v_mov_b64_e32 v[38:39], 0
	v_mov_b64_e32 v[40:41], 0
	v_mov_b64_e32 v[50:51], 0
	v_mov_b64_e32 v[52:53], 0
	v_mov_b64_e32 v[54:55], 0
	v_mov_b64_e32 v[56:57], 0
	v_mov_b64_e32 v[10:11], 0
	v_mov_b64_e32 v[12:13], 0
	v_mov_b64_e32 v[14:15], 0
	v_mov_b64_e32 v[16:17], 0
	v_mov_b64_e32 v[26:27], 0
	v_mov_b64_e32 v[28:29], 0
	v_mov_b64_e32 v[30:31], 0
	v_mov_b64_e32 v[32:33], 0
	v_mov_b64_e32 v[42:43], 0
	v_mov_b64_e32 v[44:45], 0
	v_mov_b64_e32 v[46:47], 0
	v_mov_b64_e32 v[48:49], 0
	v_mov_b64_e32 v[58:59], 0
	v_mov_b64_e32 v[60:61], 0
	v_mov_b64_e32 v[62:63], 0
	v_mov_b64_e32 v[64:65], 0
	v_mov_b64_e32 v[66:67], 0
	v_mov_b64_e32 v[68:69], 0
	v_mov_b64_e32 v[70:71], 0
	v_mov_b64_e32 v[72:73], 0
	v_mov_b64_e32 v[82:83], 0
	v_mov_b64_e32 v[84:85], 0
	v_mov_b64_e32 v[86:87], 0
	v_mov_b64_e32 v[88:89], 0
	v_mov_b64_e32 v[98:99], 0
	v_mov_b64_e32 v[100:101], 0
	v_mov_b64_e32 v[102:103], 0
	v_mov_b64_e32 v[104:105], 0
	v_mov_b64_e32 v[130:131], 0
	v_mov_b64_e32 v[132:133], 0
	v_mov_b64_e32 v[138:139], 0
	v_mov_b64_e32 v[140:141], 0
	v_mov_b64_e32 v[74:75], 0
	v_mov_b64_e32 v[76:77], 0
	v_mov_b64_e32 v[78:79], 0
	v_mov_b64_e32 v[80:81], 0
	v_mov_b64_e32 v[90:91], 0
	v_mov_b64_e32 v[92:93], 0
	v_mov_b64_e32 v[94:95], 0
	v_mov_b64_e32 v[96:97], 0
	v_mov_b64_e32 v[106:107], 0
	v_mov_b64_e32 v[108:109], 0
	v_mov_b64_e32 v[114:115], 0
	v_mov_b64_e32 v[116:117], 0
	v_mov_b64_e32 v[158:159], 0
	v_mov_b64_e32 v[160:161], 0
	v_mov_b64_e32 v[162:163], 0
	v_mov_b64_e32 v[164:165], 0
